# attention K tile LDS row stride 208->224 bytes: ds_read_b128 fragment reads become bank-conflict free
# speedup vs baseline: 1.0085x; 1.0085x over previous
.LBB0_159:
	s_and_b64 s[2:3], s[60:61], exec
	s_movk_i32 s2, 0x220
	s_cselect_b32 s19, s2, 0x200
	s_cmp_ge_i32 s9, s19
	s_cbranch_scc1 .LBB0_181
	s_waitcnt vmcnt(1)
	v_bfe_u32 v5, v160, 4, 2
	v_and_b32_e32 v4, 16, v160
	s_movk_i32 s2, 0x200
	v_and_b32_e32 v3, 15, v160
	v_ashrrev_i32_e32 v2, 1, v160
	v_lshlrev_b32_e32 v110, 4, v5
	v_mov_b32_e32 v111, v157
	v_cmp_eq_u32_e64 s[38:39], 0, v4
	v_or_b32_sdwa v4, v160, s2 dst_sel:DWORD dst_unused:UNUSED_PAD src0_sel:BYTE_0 src1_sel:DWORD
	s_mov_b32 s2, 0x2aaaaaab
	v_and_b32_e32 v108, 0xffffffe0, v2
	v_lshl_add_u64 v[0:1], s[36:37], 0, v[110:111]
	v_and_or_b32 v111, v2, 32, v3
	v_mul_hi_i32 v2, v160, s2
	v_lshrrev_b32_e32 v6, 31, v2
	v_lshrrev_b32_e32 v2, 1, v2
	v_add_u32_e32 v2, v2, v6
	v_ashrrev_i32_e32 v7, 3, v160
	s_movk_i32 s2, 0x2200
	v_lshl_add_u32 v139, v2, 1, v160
	v_lshlrev_b32_e32 v139, 4, v139
	v_mul_u32_u24_e32 v2, 0x1556, v4
	v_mad_i64_i32 v[114:115], s[2:3], v7, s2, 0
	v_lshrrev_b32_e32 v2, 16, v2
	v_and_b32_e32 v6, 7, v160
	s_movk_i32 s2, 0x100
	v_lshlrev_b32_e32 v138, 3, v5
	v_cmp_gt_u32_e64 s[40:41], 2, v5
	v_lshl_add_u32 v140, v2, 1, v4
	v_lshlrev_b32_e32 v140, 4, v140
	v_lshlrev_b32_e32 v2, 4, v6
	v_cmp_gt_i32_e64 s[42:43], s2, v160
	s_movk_i32 s2, 0x90
	v_lshlrev_b32_e32 v8, 2, v5
	v_mul_u32_u24_e32 v5, 0x60, v3
	v_mad_u64_u32 v[116:117], s[2:3], v7, s2, v[2:3]
	v_and_b32_e32 v7, 64, v197
	v_lshlrev_b32_e32 v156, 1, v5
	v_or_b32_e32 v117, v108, v3
	v_mul_u32_u24_e32 v142, 0xe0, v3
	v_mul_u32_u24_e32 v143, 0x90, v3
	v_xor_b32_e32 v3, 32, v197
	v_add_u32_e32 v7, 64, v7
	v_lshl_add_u64 v[118:119], v[0:1], 0, v[156:157]
	v_or_b32_e32 v0, v114, v2
	v_mov_b32_e32 v1, v115
	v_cmp_lt_i32_e32 vcc, v3, v7
	v_lshl_add_u64 v[0:1], s[26:27], 0, v[0:1]
	s_mov_b64 s[2:3], 0x104e0080
	v_cndmask_b32_e32 v3, v197, v3, vcc
	v_lshl_add_u64 v[120:121], v[0:1], 0, s[2:3]
	v_mov_b32_e32 v0, 4
	v_lshlrev_b32_e32 v144, 2, v3
	v_xor_b32_e32 v3, 16, v197
	v_lshlrev_b32_sdwa v156, v0, v160 dst_sel:DWORD dst_unused:UNUSED_PAD src0_sel:DWORD src1_sel:BYTE_0
	v_ashrrev_i32_e32 v161, 31, v160
	v_cmp_lt_i32_e32 vcc, v3, v7
	v_lshl_add_u64 v[0:1], s[26:27], 0, v[156:157]
	s_mov_b64 s[2:3], 0xeb65000
	v_lshlrev_b32_e32 v4, 3, v4
	v_lshlrev_b32_e32 v6, 3, v6
	v_cndmask_b32_e32 v3, v197, v3, vcc
	v_lshl_add_u64 v[122:123], v[0:1], 0, s[2:3]
	v_lshl_add_u64 v[0:1], v[160:161], 4, s[26:27]
	s_mov_b64 s[2:3], 0xeb63000
	v_ashrrev_i32_e32 v109, 31, v108
	v_lshlrev_b64 v[112:113], 3, v[160:161]
	v_or_b32_e32 v141, 16, v111
	v_lshlrev_b32_e32 v145, 2, v3
	v_lshl_add_u64 v[124:125], v[0:1], 0, s[2:3]
	v_lshlrev_b32_e32 v146, 1, v4
	v_lshlrev_b32_e32 v156, 1, v6
	v_lshlrev_b32_e32 v126, 1, v8
	s_branch .LBB0_162
.LBB0_161:
	s_setprio 0
	v_add3_u32 v96, s10, v110, v142
	ds_read_b128 v[64:67], v96
	ds_read_b128 v[68:71], v96 offset:64
	ds_read_b128 v[72:75], v96 offset:128
	v_mov_b32_e32 v131, v130
	v_mov_b32_e32 v129, v128
	s_waitcnt lgkmcnt(2)
	v_mfma_f32_16x16x32_bf16 v[76:79], v[64:67], v[0:3], 0
	s_mov_b32 s53, s52
	s_mov_b32 s54, s52
	s_mov_b32 s55, s52
	v_mfma_f32_16x16x32_bf16 v[64:67], v[64:67], v[8:11], 0
	v_mov_b32_e32 v127, v157
	s_add_i32 s9, s9, s18
	s_waitcnt lgkmcnt(1)
	v_mfma_f32_16x16x32_bf16 v[76:79], v[68:71], v[4:7], v[76:79]
	v_mfma_f32_16x16x32_bf16 v[64:67], v[68:71], v[12:15], v[64:67]
	s_waitcnt lgkmcnt(0)
	v_mfma_f32_16x16x32_bf16 v[76:79], v[72:75], v[16:19], v[76:79]
	v_mfma_f32_16x16x32_bf16 v[64:67], v[72:75], v[20:23], v[64:67]
	ds_read_b128 v[68:71], v96 offset:3584
	ds_read_b128 v[72:75], v96 offset:3648
	ds_read_b128 v[80:83], v96 offset:3712
	s_waitcnt lgkmcnt(2)
	v_mfma_f32_16x16x32_bf16 v[84:87], v[68:71], v[0:3], 0
	v_mfma_f32_16x16x32_bf16 v[68:71], v[68:71], v[8:11], 0
	s_waitcnt lgkmcnt(1)
	v_mfma_f32_16x16x32_bf16 v[84:87], v[72:75], v[4:7], v[84:87]
	v_mfma_f32_16x16x32_bf16 v[68:71], v[72:75], v[12:15], v[68:71]
	s_waitcnt lgkmcnt(0)
	v_mfma_f32_16x16x32_bf16 v[84:87], v[80:83], v[16:19], v[84:87]
	v_mfma_f32_16x16x32_bf16 v[68:71], v[80:83], v[20:23], v[68:71]
	ds_read_b128 v[72:75], v96 offset:7168
	ds_read_b128 v[80:83], v96 offset:7232
	ds_read_b128 v[88:91], v96 offset:7296
	s_waitcnt lgkmcnt(2)
	v_mfma_f32_16x16x32_bf16 v[92:95], v[72:75], v[0:3], 0
	v_mfma_f32_16x16x32_bf16 v[72:75], v[72:75], v[8:11], 0
	s_waitcnt lgkmcnt(1)
	v_mfma_f32_16x16x32_bf16 v[92:95], v[80:83], v[4:7], v[92:95]
	v_mfma_f32_16x16x32_bf16 v[72:75], v[80:83], v[12:15], v[72:75]
	s_waitcnt lgkmcnt(0)
	v_mfma_f32_16x16x32_bf16 v[92:95], v[88:91], v[16:19], v[92:95]
	v_mfma_f32_16x16x32_bf16 v[72:75], v[88:91], v[20:23], v[72:75]
	ds_read_b128 v[80:83], v96 offset:10752
	ds_read_b128 v[88:91], v96 offset:10816
	ds_read_b128 v[96:99], v96 offset:10880
	s_waitcnt lgkmcnt(2)
	v_mfma_f32_16x16x32_bf16 v[0:3], v[80:83], v[0:3], 0
	s_waitcnt lgkmcnt(1)
	v_mfma_f32_16x16x32_bf16 v[0:3], v[88:91], v[4:7], v[0:3]
	v_mfma_f32_16x16x32_bf16 v[4:7], v[80:83], v[8:11], 0
	v_add_f32_e64 v8, v76, -v130
	v_add_f32_e64 v9, v77, -v131
	v_pk_add_f32 v[10:11], v[78:79], v[130:131] neg_lo:[0,1] neg_hi:[0,1]
	s_waitcnt lgkmcnt(0)
	v_mfma_f32_16x16x32_bf16 v[0:3], v[96:99], v[16:19], v[0:3]
	v_mfma_f32_16x16x32_bf16 v[4:7], v[88:91], v[12:15], v[4:7]
	v_exp_f32_e32 v12, v8
	v_exp_f32_e32 v13, v9
	v_exp_f32_e32 v14, v10
	v_exp_f32_e32 v15, v11
	v_pk_add_f32 v[8:9], v[84:85], v[130:131] neg_lo:[0,1] neg_hi:[0,1]
	v_pk_add_f32 v[10:11], v[86:87], v[130:131] neg_lo:[0,1] neg_hi:[0,1]
	s_nop 0
	v_pk_add_f32 v[0:1], v[0:1], v[130:131] neg_lo:[0,1] neg_hi:[0,1]
	v_pk_add_f32 v[2:3], v[2:3], v[130:131] neg_lo:[0,1] neg_hi:[0,1]
	v_mfma_f32_16x16x32_bf16 v[4:7], v[96:99], v[20:23], v[4:7]
	v_exp_f32_e32 v18, v8
	v_exp_f32_e32 v19, v9
	v_exp_f32_e32 v20, v10
	v_exp_f32_e32 v21, v11
	v_pk_add_f32 v[8:9], v[92:93], v[130:131] neg_lo:[0,1] neg_hi:[0,1]
	v_pk_add_f32 v[10:11], v[94:95], v[130:131] neg_lo:[0,1] neg_hi:[0,1]
	v_exp_f32_e32 v0, v0
	v_exp_f32_e32 v1, v1
	v_exp_f32_e32 v2, v2
	v_exp_f32_e32 v3, v3
	v_exp_f32_e32 v8, v8
	v_exp_f32_e32 v9, v9
	v_exp_f32_e32 v10, v10
	v_exp_f32_e32 v11, v11
	v_cvt_pk_bf16_f32 v16, v12, v13
	v_cvt_pk_bf16_f32 v17, v14, v15
	v_cvt_pk_bf16_f32 v18, v18, v19
	v_cvt_pk_bf16_f32 v19, v20, v21
	v_cvt_pk_bf16_f32 v20, v8, v9
	v_cvt_pk_bf16_f32 v21, v10, v11
	v_cvt_pk_bf16_f32 v22, v0, v1
	v_cvt_pk_bf16_f32 v23, v2, v3
	v_pk_add_f32 v[0:1], v[64:65], v[128:129] neg_lo:[0,1] neg_hi:[0,1]
	v_pk_add_f32 v[2:3], v[66:67], v[128:129] neg_lo:[0,1] neg_hi:[0,1]
	v_exp_f32_e32 v8, v0
	v_exp_f32_e32 v9, v1
	v_exp_f32_e32 v10, v2
	v_exp_f32_e32 v11, v3
	v_pk_add_f32 v[0:1], v[68:69], v[128:129] neg_lo:[0,1] neg_hi:[0,1]
	v_pk_add_f32 v[2:3], v[70:71], v[128:129] neg_lo:[0,1] neg_hi:[0,1]
	v_exp_f32_e32 v12, v0
	v_exp_f32_e32 v13, v1
	v_exp_f32_e32 v14, v2
	v_exp_f32_e32 v15, v3
	v_pk_add_f32 v[0:1], v[72:73], v[128:129] neg_lo:[0,1] neg_hi:[0,1]
	v_pk_add_f32 v[2:3], v[74:75], v[128:129] neg_lo:[0,1] neg_hi:[0,1]
	v_exp_f32_e32 v68, v0
	v_exp_f32_e32 v69, v1
	v_exp_f32_e32 v70, v2
	v_exp_f32_e32 v71, v3
	v_pk_add_f32 v[0:1], v[4:5], v[128:129] neg_lo:[0,1] neg_hi:[0,1]
	v_pk_add_f32 v[2:3], v[6:7], v[128:129] neg_lo:[0,1] neg_hi:[0,1]
	v_add3_u32 v72, s10, v138, v143
	v_exp_f32_e32 v0, v0
	v_exp_f32_e32 v1, v1
	v_exp_f32_e32 v2, v2
	v_exp_f32_e32 v3, v3
	v_cvt_pk_bf16_f32 v64, v8, v9
	v_add_u32_e32 v8, 0x3400, v72
	v_cvt_pk_bf16_f32 v65, v10, v11
	v_cvt_pk_bf16_f32 v66, v12, v13
	v_cvt_pk_bf16_f32 v67, v14, v15
	v_cvt_pk_bf16_f32 v68, v68, v69
	v_cvt_pk_bf16_f32 v69, v70, v71
	v_cvt_pk_bf16_f32 v70, v0, v1
	v_cvt_pk_bf16_f32 v71, v2, v3
	ds_read2_b64 v[0:3], v8 offset0:128 offset1:132
	ds_read2_b64 v[8:11], v8 offset0:136 offset1:140
	s_waitcnt lgkmcnt(1)
	v_mfma_f32_16x16x32_bf16 v[4:7], v[0:3], v[16:19], v[60:63]
	v_add_u32_e32 v12, 0x3c00, v72
	s_lshl_b32 s10, s24, 7
	s_cmp_ge_i32 s9, s19
	v_mfma_f32_16x16x32_bf16 v[0:3], v[0:3], v[64:67], v[56:59]
	s_waitcnt lgkmcnt(0)
	v_mfma_f32_16x16x32_bf16 v[56:59], v[8:11], v[20:23], v[4:7]
	s_nop 2
	ds_read2_b64 v[4:7], v12 offset0:160 offset1:164
	ds_read2_b64 v[12:15], v12 offset0:168 offset1:172
	v_mfma_f32_16x16x32_bf16 v[0:3], v[8:11], v[68:71], v[0:3]
	s_waitcnt lgkmcnt(1)
	v_mfma_f32_16x16x32_bf16 v[8:11], v[4:7], v[16:19], v[52:55]
	s_nop 2
	v_add_u32_e32 v52, 0x4400, v72
	v_mfma_f32_16x16x32_bf16 v[4:7], v[4:7], v[64:67], v[48:51]
	s_waitcnt lgkmcnt(0)
	v_mfma_f32_16x16x32_bf16 v[48:51], v[12:15], v[20:23], v[8:11]
	s_nop 2
	ds_read2_b64 v[8:11], v52 offset0:192 offset1:196
	v_mfma_f32_16x16x32_bf16 v[4:7], v[12:15], v[68:71], v[4:7]
	s_waitcnt lgkmcnt(0)
	v_mfma_f32_16x16x32_bf16 v[12:15], v[8:11], v[16:19], v[44:47]
	v_mfma_f32_16x16x32_bf16 v[8:11], v[8:11], v[64:67], v[40:43]
	s_nop 2
	ds_read2_b64 v[40:43], v52 offset0:200 offset1:204
	s_waitcnt lgkmcnt(0)
	v_mfma_f32_16x16x32_bf16 v[44:47], v[40:43], v[20:23], v[12:15]
	v_mfma_f32_16x16x32_bf16 v[12:15], v[40:43], v[68:71], v[8:11]
	v_add_u32_e32 v40, 0x4c00, v72
	s_nop 1
	ds_read2_b64 v[8:11], v40 offset0:224 offset1:228
	ds_read2_b64 v[40:43], v40 offset0:232 offset1:236
	s_waitcnt lgkmcnt(1)
	v_mfma_f32_16x16x32_bf16 v[36:39], v[8:11], v[16:19], v[36:39]
	s_waitcnt lgkmcnt(0)
	s_barrier
	v_mfma_f32_16x16x32_bf16 v[8:11], v[8:11], v[64:67], v[32:35]
	v_mfma_f32_16x16x32_bf16 v[32:35], v[40:43], v[20:23], v[36:39]
	s_nop 3
	v_mov_b64_e32 v[36:37], s[52:53]
	v_mov_b64_e32 v[38:39], s[54:55]
	v_mfma_f32_16x16x32_bf16 v[8:11], v[40:43], v[68:71], v[8:11]
	s_nop 0
	v_mfma_f32_16x16x32_bf16 v[16:19], v[36:39], v[16:19], v[28:31]
	v_mfma_f32_16x16x32_bf16 v[24:27], v[36:39], v[64:67], v[24:27]
	v_mfma_f32_16x16x32_bf16 v[16:19], v[36:39], v[20:23], v[16:19]
	v_mfma_f32_16x16x32_bf16 v[18:21], v[36:39], v[68:71], v[24:27]
	s_nop 6
	v_div_scale_f32 v17, s[2:3], v16, v16, 1.0
	v_rcp_f32_e32 v19, v17
	v_add_u32_e32 v20, s25, v117
	v_fma_f32 v21, -v17, v19, 1.0
	v_fmac_f32_e32 v19, v21, v19
	v_div_scale_f32 v21, vcc, 1.0, v16, 1.0
	v_mul_f32_e32 v22, v21, v19
	v_fma_f32 v23, -v17, v22, v21
	v_fmac_f32_e32 v22, v23, v19
	v_fma_f32 v17, -v17, v22, v21
	v_ashrrev_i32_e32 v21, 31, v20
	v_div_fmas_f32 v17, v17, v19, v22
	v_lshlrev_b64 v[22:23], 11, v[20:21]
	v_div_fixup_f32 v16, v17, v16, 1.0
	v_lshl_add_u64 v[22:23], s[58:59], 0, v[22:23]
	v_lshl_add_u64 v[22:23], v[22:23], 0, s[10:11]
	v_pk_mul_f32 v[26:27], v[56:57], v[16:17] op_sel_hi:[1,0]
	v_lshl_add_u64 v[22:23], v[22:23], 0, v[126:127]
	v_pk_mul_f32 v[24:25], v[58:59], v[16:17] op_sel_hi:[1,0]
	v_cvt_pk_bf16_f32 v26, v26, v27
	s_nop 0
	v_cvt_pk_bf16_f32 v27, v24, v25
	global_store_dwordx2 v[22:23], v[26:27], off offset:512
	v_pk_mul_f32 v[26:27], v[48:49], v[16:17] op_sel_hi:[1,0]
	v_pk_mul_f32 v[24:25], v[50:51], v[16:17] op_sel_hi:[1,0]
	v_cvt_pk_bf16_f32 v26, v26, v27
	s_nop 0
	v_cvt_pk_bf16_f32 v27, v24, v25
	global_store_dwordx2 v[22:23], v[26:27], off offset:544
	v_pk_mul_f32 v[24:25], v[46:47], v[16:17] op_sel_hi:[1,0]
	v_pk_mul_f32 v[26:27], v[44:45], v[16:17] op_sel_hi:[1,0]
	s_nop 0
	v_cvt_pk_bf16_f32 v26, v26, v27
	v_cvt_pk_bf16_f32 v27, v24, v25
	v_pk_mul_f32 v[24:25], v[34:35], v[16:17] op_sel_hi:[1,0]
	v_pk_mul_f32 v[16:17], v[32:33], v[16:17] op_sel_hi:[1,0]
	global_store_dwordx2 v[22:23], v[26:27], off offset:576
	v_cvt_pk_bf16_f32 v16, v16, v17
	v_cvt_pk_bf16_f32 v17, v24, v25
	global_store_dwordx2 v[22:23], v[16:17], off offset:608
	v_div_scale_f32 v16, s[2:3], v18, v18, 1.0
	v_rcp_f32_e32 v17, v16
	s_nop 0
	v_fma_f32 v19, -v16, v17, 1.0
	v_fmac_f32_e32 v17, v19, v17
	v_div_scale_f32 v19, vcc, 1.0, v18, 1.0
	v_mul_f32_e32 v21, v19, v17
	v_fma_f32 v22, -v16, v21, v19
	v_fmac_f32_e32 v21, v22, v17
	v_fma_f32 v16, -v16, v21, v19
	v_div_fmas_f32 v16, v16, v17, v21
	v_div_fixup_f32 v16, v16, v18, 1.0
	v_add_u32_e32 v18, 16, v20
	v_ashrrev_i32_e32 v19, 31, v18
	v_lshlrev_b64 v[18:19], 11, v[18:19]
	v_lshl_add_u64 v[18:19], s[58:59], 0, v[18:19]
	v_lshl_add_u64 v[18:19], v[18:19], 0, s[10:11]
	v_pk_mul_f32 v[2:3], v[2:3], v[16:17] op_sel_hi:[1,0]
	v_pk_mul_f32 v[0:1], v[0:1], v[16:17] op_sel_hi:[1,0]
	v_lshl_add_u64 v[18:19], v[18:19], 0, v[126:127]
	v_cvt_pk_bf16_f32 v0, v0, v1
	v_cvt_pk_bf16_f32 v1, v2, v3
	v_pk_mul_f32 v[2:3], v[4:5], v[16:17] op_sel_hi:[1,0]
	global_store_dwordx2 v[18:19], v[0:1], off offset:512
	v_pk_mul_f32 v[0:1], v[6:7], v[16:17] op_sel_hi:[1,0]
	v_cvt_pk_bf16_f32 v2, v2, v3
	s_nop 0
	v_cvt_pk_bf16_f32 v3, v0, v1
	global_store_dwordx2 v[18:19], v[2:3], off offset:544
	v_pk_mul_f32 v[2:3], v[12:13], v[16:17] op_sel_hi:[1,0]
	v_pk_mul_f32 v[0:1], v[14:15], v[16:17] op_sel_hi:[1,0]
	v_cvt_pk_bf16_f32 v2, v2, v3
	s_nop 0
	v_cvt_pk_bf16_f32 v3, v0, v1
	global_store_dwordx2 v[18:19], v[2:3], off offset:576
	v_pk_mul_f32 v[2:3], v[8:9], v[16:17] op_sel_hi:[1,0]
	v_pk_mul_f32 v[0:1], v[10:11], v[16:17] op_sel_hi:[1,0]
	v_cvt_pk_bf16_f32 v2, v2, v3
	s_nop 0
	v_cvt_pk_bf16_f32 v3, v0, v1
	global_store_dwordx2 v[18:19], v[2:3], off offset:608
	s_cbranch_scc1 .LBB0_181

.LBB0_173:
	s_or_b64 exec, exec, s[6:7]
	s_add_i32 s6, s34, 1
	s_waitcnt vmcnt(1)
	v_add_u32_e32 v24, 0, v116
	s_add_u32 s34, s21, s35
	v_mov_b32_e32 v26, v157
	v_mov_b32_e32 v27, v157
	s_waitcnt vmcnt(0)
	ds_write_b128 v24, v[28:31] offset:14336
	s_addc_u32 s35, s10, 0
	v_mov_b32_e32 v24, v157
	v_mov_b32_e32 v25, v157
	v_mov_b64_e32 v[30:31], v[26:27]
	v_mov_b64_e32 v[34:35], v[26:27]
	v_mov_b64_e32 v[38:39], v[26:27]
	v_mov_b64_e32 v[42:43], v[26:27]
	v_mov_b64_e32 v[46:47], v[26:27]
	v_mov_b64_e32 v[50:51], v[26:27]
	v_mov_b64_e32 v[54:55], v[26:27]
	v_mov_b64_e32 v[58:59], v[26:27]
	v_mov_b64_e32 v[62:63], v[26:27]
	v_lshl_add_u64 v[132:133], v[120:121], 0, s[34:35]
	v_lshl_add_u64 v[134:135], v[122:123], 0, s[2:3]
	v_lshl_add_u64 v[136:137], v[124:125], 0, s[2:3]
	s_mov_b32 s7, 0
	v_mov_b32_e32 v128, 0xf149f2ca
	v_mov_b64_e32 v[28:29], v[24:25]
	v_mov_b64_e32 v[32:33], v[24:25]
	v_mov_b64_e32 v[36:37], v[24:25]
	v_mov_b64_e32 v[40:41], v[24:25]
	v_mov_b64_e32 v[44:45], v[24:25]
	v_mov_b64_e32 v[48:49], v[24:25]
	v_mov_b64_e32 v[52:53], v[24:25]
	v_mov_b64_e32 v[56:57], v[24:25]
	v_mov_b64_e32 v[60:61], v[24:25]
	v_mov_b32_e32 v130, 0xf149f2ca
	s_waitcnt lgkmcnt(0)
	s_barrier
	v_mov_b32_e32 v250, s52
	v_mov_b32_e32 v251, s52
	v_mov_b32_e32 v252, s52
	v_mov_b32_e32 v253, s52
	v_readfirstlane_b32 s2, v160
	s_cmpk_ge_u32 s2, 0x100
	s_cbranch_scc0 .Lattn_noprio
	s_setprio 1

.LBB0_175:
	s_bitcmp1_b32 s7, 0
	s_cselect_b32 s2, 0x5c00, 0
	s_add_i32 s10, s2, 0
	v_add3_u32 v104, s10, v110, v142
	v_add3_u32 v147, s10, v138, v143
	ds_read_b128 v[162:165], v104
	ds_read_b128 v[166:169], v104 offset:64
	ds_read_b128 v[170:173], v104 offset:128
	ds_read_b128 v[174:177], v104 offset:3584
	ds_read_b128 v[178:181], v104 offset:3648
	ds_read_b128 v[182:185], v104 offset:3712
	ds_read_b128 v[186:189], v104 offset:7168
	ds_read_b128 v[214:217], v104 offset:7232
	ds_read_b128 v[218:221], v104 offset:7296
	ds_read_b128 v[222:225], v104 offset:10752
	ds_read_b128 v[226:229], v104 offset:10816
	ds_read_b128 v[230:233], v104 offset:10880
	global_load_dwordx4 v[72:75], v[136:137], off
	global_load_dwordx4 v[68:71], v[134:135], off
	global_load_dwordx4 v[64:67], v[132:133], off
	s_and_b32 s21, s7, 15
	s_cbranch_scc0 .Lattn_refresh
	s_waitcnt lgkmcnt(11)
	v_mfma_f32_16x16x32_bf16 v[92:95], v[162:165], v[0:3], v[148:151]
	v_mfma_f32_16x16x32_bf16 v[76:79], v[162:165], v[8:11], v[152:155]
	ds_read_b64 v[234:235], v147 offset:14336
	ds_read_b64 v[236:237], v147 offset:14368
	s_waitcnt lgkmcnt(12)
	v_mfma_f32_16x16x32_bf16 v[92:95], v[166:169], v[4:7], v[92:95]
	v_mfma_f32_16x16x32_bf16 v[76:79], v[166:169], v[12:15], v[76:79]
	ds_read_b64 v[238:239], v147 offset:14400
	ds_read_b64 v[240:241], v147 offset:14432
	s_waitcnt lgkmcnt(13)
	v_mfma_f32_16x16x32_bf16 v[92:95], v[170:173], v[16:19], v[92:95]
	v_mfma_f32_16x16x32_bf16 v[76:79], v[170:173], v[20:23], v[76:79]
	ds_read_b64 v[242:243], v147 offset:16640
	ds_read_b64 v[244:245], v147 offset:16672
	s_waitcnt lgkmcnt(14)
	v_mfma_f32_16x16x32_bf16 v[96:99], v[174:177], v[0:3], v[148:151]
	v_mfma_f32_16x16x32_bf16 v[80:83], v[174:177], v[8:11], v[152:155]
	ds_read_b64 v[246:247], v147 offset:16704
	s_waitcnt lgkmcnt(14)
	v_mfma_f32_16x16x32_bf16 v[96:99], v[178:181], v[4:7], v[96:99]
	v_mfma_f32_16x16x32_bf16 v[80:83], v[178:181], v[12:15], v[80:83]
	ds_read_b64 v[248:249], v147 offset:16736
	s_waitcnt lgkmcnt(14)
	v_mfma_f32_16x16x32_bf16 v[96:99], v[182:185], v[16:19], v[96:99]
	v_mfma_f32_16x16x32_bf16 v[80:83], v[182:185], v[20:23], v[80:83]
	ds_read_b64 v[162:163], v147 offset:18944
	s_waitcnt lgkmcnt(14)
	v_mfma_f32_16x16x32_bf16 v[100:103], v[186:189], v[0:3], v[148:151]
	v_mfma_f32_16x16x32_bf16 v[84:87], v[186:189], v[8:11], v[152:155]
	ds_read_b64 v[164:165], v147 offset:18976
	s_waitcnt lgkmcnt(14)
	v_mfma_f32_16x16x32_bf16 v[100:103], v[214:217], v[4:7], v[100:103]
	v_mfma_f32_16x16x32_bf16 v[84:87], v[214:217], v[12:15], v[84:87]
	ds_read_b64 v[166:167], v147 offset:19008
	s_waitcnt lgkmcnt(14)
	v_mfma_f32_16x16x32_bf16 v[100:103], v[218:221], v[16:19], v[100:103]
	v_mfma_f32_16x16x32_bf16 v[84:87], v[218:221], v[20:23], v[84:87]
	ds_read_b64 v[168:169], v147 offset:19040
	s_waitcnt lgkmcnt(14)
	v_mfma_f32_16x16x32_bf16 v[104:107], v[222:225], v[0:3], v[148:151]
	v_mfma_f32_16x16x32_bf16 v[88:91], v[222:225], v[8:11], v[152:155]
	ds_read_b64 v[170:171], v147 offset:21248
	s_waitcnt lgkmcnt(14)
	v_mfma_f32_16x16x32_bf16 v[104:107], v[226:229], v[4:7], v[104:107]
	v_mfma_f32_16x16x32_bf16 v[88:91], v[226:229], v[12:15], v[88:91]
	ds_read_b64 v[172:173], v147 offset:21280
	s_waitcnt lgkmcnt(14)
	v_mfma_f32_16x16x32_bf16 v[104:107], v[230:233], v[16:19], v[104:107]
	v_mfma_f32_16x16x32_bf16 v[88:91], v[230:233], v[20:23], v[88:91]
	s_waitcnt lgkmcnt(13)
	ds_read_b64 v[174:175], v147 offset:21312
	ds_read_b64 v[176:177], v147 offset:21344
.Lattn_sm:
	v_exp_f32_e32 v92, v92
	v_exp_f32_e32 v93, v93
	v_exp_f32_e32 v94, v94
	v_exp_f32_e32 v95, v95
	v_exp_f32_e32 v96, v96
	v_exp_f32_e32 v97, v97
	v_exp_f32_e32 v98, v98
	v_exp_f32_e32 v99, v99
	v_exp_f32_e32 v100, v100
	v_exp_f32_e32 v101, v101
	v_exp_f32_e32 v102, v102
	v_exp_f32_e32 v103, v103
	v_exp_f32_e32 v104, v104
	v_exp_f32_e32 v105, v105
	v_exp_f32_e32 v106, v106
	v_exp_f32_e32 v107, v107
	v_cvt_pk_bf16_f32 v92, v92, v93
	v_cvt_pk_bf16_f32 v93, v94, v95
	v_cvt_pk_bf16_f32 v94, v96, v97
	v_cvt_pk_bf16_f32 v95, v98, v99
	v_cvt_pk_bf16_f32 v96, v100, v101
	v_cvt_pk_bf16_f32 v97, v102, v103
	v_cvt_pk_bf16_f32 v98, v104, v105
	v_cvt_pk_bf16_f32 v99, v106, v107
	v_exp_f32_e32 v76, v76
	v_exp_f32_e32 v77, v77
	v_exp_f32_e32 v78, v78
	v_exp_f32_e32 v79, v79
	v_exp_f32_e32 v80, v80
	v_exp_f32_e32 v81, v81
	v_exp_f32_e32 v82, v82
	v_exp_f32_e32 v83, v83
	v_exp_f32_e32 v84, v84
	v_exp_f32_e32 v85, v85
	v_exp_f32_e32 v86, v86
	v_exp_f32_e32 v87, v87
	v_exp_f32_e32 v88, v88
	v_exp_f32_e32 v89, v89
	v_exp_f32_e32 v90, v90
	v_exp_f32_e32 v91, v91
	v_cvt_pk_bf16_f32 v76, v76, v77
	v_cvt_pk_bf16_f32 v77, v78, v79
	v_cvt_pk_bf16_f32 v78, v80, v81
	v_cvt_pk_bf16_f32 v79, v82, v83
	v_cvt_pk_bf16_f32 v80, v84, v85
	v_cvt_pk_bf16_f32 v81, v86, v87
	v_cvt_pk_bf16_f32 v82, v88, v89
	v_cvt_pk_bf16_f32 v83, v90, v91
	s_add_i32 s7, s7, 1
	s_bitcmp1_b32 s7, 0
	s_cselect_b32 s2, 0x5c00, 0
	s_add_i32 s10, s2, 0
	v_add_u32_e32 v127, s10, v139
	v_add_u32_e32 v129, s10, v140
	v_add_u32_e32 v131, s10, v116
	s_waitcnt vmcnt(2)
	ds_write_b128 v127, v[72:75]
	s_waitcnt vmcnt(0)
	ds_write_b128 v131, v[64:67] offset:14336
	s_and_b64 vcc, exec, s[42:43]
	s_cbranch_vccz .Lattn_skipw
	ds_write_b128 v129, v[68:71]

.Lattn_refresh:
	s_waitcnt lgkmcnt(11)
	v_mfma_f32_16x16x32_bf16 v[92:95], v[162:165], v[0:3], 0
	v_mfma_f32_16x16x32_bf16 v[76:79], v[162:165], v[8:11], 0
	ds_read_b64 v[234:235], v147 offset:14336
	ds_read_b64 v[236:237], v147 offset:14368
	s_waitcnt lgkmcnt(12)
	v_mfma_f32_16x16x32_bf16 v[92:95], v[166:169], v[4:7], v[92:95]
	v_mfma_f32_16x16x32_bf16 v[76:79], v[166:169], v[12:15], v[76:79]
	ds_read_b64 v[238:239], v147 offset:14400
	ds_read_b64 v[240:241], v147 offset:14432
	s_waitcnt lgkmcnt(13)
	v_mfma_f32_16x16x32_bf16 v[92:95], v[170:173], v[16:19], v[92:95]
	v_mfma_f32_16x16x32_bf16 v[76:79], v[170:173], v[20:23], v[76:79]
	ds_read_b64 v[242:243], v147 offset:16640
	ds_read_b64 v[244:245], v147 offset:16672
	s_waitcnt lgkmcnt(14)
	v_mfma_f32_16x16x32_bf16 v[96:99], v[174:177], v[0:3], 0
	v_mfma_f32_16x16x32_bf16 v[80:83], v[174:177], v[8:11], 0
	ds_read_b64 v[246:247], v147 offset:16704
	s_waitcnt lgkmcnt(14)
	v_mfma_f32_16x16x32_bf16 v[96:99], v[178:181], v[4:7], v[96:99]
	v_mfma_f32_16x16x32_bf16 v[80:83], v[178:181], v[12:15], v[80:83]
	ds_read_b64 v[248:249], v147 offset:16736
	s_waitcnt lgkmcnt(14)
	v_mfma_f32_16x16x32_bf16 v[96:99], v[182:185], v[16:19], v[96:99]
	v_mfma_f32_16x16x32_bf16 v[80:83], v[182:185], v[20:23], v[80:83]
	ds_read_b64 v[162:163], v147 offset:18944
	s_waitcnt lgkmcnt(14)
	v_mfma_f32_16x16x32_bf16 v[100:103], v[186:189], v[0:3], 0
	v_mfma_f32_16x16x32_bf16 v[84:87], v[186:189], v[8:11], 0
	ds_read_b64 v[164:165], v147 offset:18976
	s_waitcnt lgkmcnt(14)
	v_mfma_f32_16x16x32_bf16 v[100:103], v[214:217], v[4:7], v[100:103]
	v_mfma_f32_16x16x32_bf16 v[84:87], v[214:217], v[12:15], v[84:87]
	ds_read_b64 v[166:167], v147 offset:19008
	s_waitcnt lgkmcnt(14)
	v_mfma_f32_16x16x32_bf16 v[100:103], v[218:221], v[16:19], v[100:103]
	v_mfma_f32_16x16x32_bf16 v[84:87], v[218:221], v[20:23], v[84:87]
	ds_read_b64 v[168:169], v147 offset:19040
	s_waitcnt lgkmcnt(14)
	v_mfma_f32_16x16x32_bf16 v[104:107], v[222:225], v[0:3], 0
	v_mfma_f32_16x16x32_bf16 v[88:91], v[222:225], v[8:11], 0
	ds_read_b64 v[170:171], v147 offset:21248
	s_waitcnt lgkmcnt(14)
	v_mfma_f32_16x16x32_bf16 v[104:107], v[226:229], v[4:7], v[104:107]
	v_mfma_f32_16x16x32_bf16 v[88:91], v[226:229], v[12:15], v[88:91]
	ds_read_b64 v[172:173], v147 offset:21280
	s_waitcnt lgkmcnt(14)
	v_mfma_f32_16x16x32_bf16 v[104:107], v[230:233], v[16:19], v[104:107]
	v_mfma_f32_16x16x32_bf16 v[88:91], v[230:233], v[20:23], v[88:91]
	s_waitcnt lgkmcnt(13)
	ds_read_b64 v[174:175], v147 offset:21312
	ds_read_b64 v[176:177], v147 offset:21344
	s_nop 7
	v_max_f32_e32 v127, v93, v93
	v_max_f32_e32 v129, v92, v92
	v_max_f32_e32 v127, v129, v127
	v_max_f32_e32 v129, v95, v95
	v_max_f32_e32 v131, v94, v94
	v_max_f32_e32 v129, v131, v129
	v_max_f32_e32 v131, v99, v99
	v_max_f32_e32 v147, v98, v98
	v_max_f32_e32 v131, v147, v131
	v_max3_f32 v131, v96, v97, v131
	v_max3_f32 v127, v127, v129, v131
	v_max_f32_e32 v129, v103, v103
	v_max_f32_e32 v131, v102, v102
	v_max_f32_e32 v129, v131, v129
	v_max_f32_e32 v131, v107, v107
	v_max_f32_e32 v147, v106, v106
	v_max_f32_e32 v131, v147, v131
	v_max3_f32 v129, v100, v101, v129
	v_max3_f32 v131, v104, v105, v131
	v_max3_f32 v127, v127, v129, v131
	ds_bpermute_b32 v129, v145, v127
	s_waitcnt lgkmcnt(0)
	v_max_f32_e32 v129, v129, v129
	v_max_f32_e32 v127, v127, v129
	ds_bpermute_b32 v129, v144, v127
	s_waitcnt lgkmcnt(0)
	v_max3_f32 v127, v130, v127, v129
	v_sub_f32_e32 v129, v130, v127
	v_exp_f32_e32 v130, v129
	s_nop 0
	v_pk_mul_f32 v[62:63], v[62:63], v[130:131] op_sel_hi:[1,0]
	v_pk_mul_f32 v[60:61], v[60:61], v[130:131] op_sel_hi:[1,0]
	v_pk_mul_f32 v[54:55], v[54:55], v[130:131] op_sel_hi:[1,0]
	v_pk_mul_f32 v[52:53], v[52:53], v[130:131] op_sel_hi:[1,0]
	v_pk_mul_f32 v[46:47], v[46:47], v[130:131] op_sel_hi:[1,0]
	v_pk_mul_f32 v[44:45], v[44:45], v[130:131] op_sel_hi:[1,0]
	v_pk_mul_f32 v[38:39], v[38:39], v[130:131] op_sel_hi:[1,0]
	v_pk_mul_f32 v[36:37], v[36:37], v[130:131] op_sel_hi:[1,0]
	v_pk_mul_f32 v[30:31], v[30:31], v[130:131] op_sel_hi:[1,0]
	v_pk_mul_f32 v[28:29], v[28:29], v[130:131] op_sel_hi:[1,0]
	v_mov_b32_e32 v130, v127
	v_xor_b32_e32 v148, 0x80000000, v127
	v_xor_b32_e32 v149, 0x80000000, v127
	v_xor_b32_e32 v150, 0x80000000, v127
	v_xor_b32_e32 v151, 0x80000000, v127
	v_max_f32_e32 v127, v77, v77
	v_max_f32_e32 v129, v76, v76
	v_max_f32_e32 v127, v129, v127
	v_max_f32_e32 v129, v79, v79
	v_max_f32_e32 v131, v78, v78
	v_max_f32_e32 v129, v131, v129
	v_max_f32_e32 v131, v83, v83
	v_max_f32_e32 v147, v82, v82
	v_max_f32_e32 v131, v147, v131
	v_max3_f32 v131, v80, v81, v131
	v_max3_f32 v127, v127, v129, v131
	v_max_f32_e32 v129, v87, v87
	v_max_f32_e32 v131, v86, v86
	v_max_f32_e32 v129, v131, v129
	v_max_f32_e32 v131, v91, v91
	v_max_f32_e32 v147, v90, v90
	v_max_f32_e32 v131, v147, v131
	v_max3_f32 v129, v84, v85, v129
	v_max3_f32 v131, v88, v89, v131
	v_max3_f32 v127, v127, v129, v131
	ds_bpermute_b32 v129, v145, v127
	s_waitcnt lgkmcnt(0)
	v_max_f32_e32 v129, v129, v129
	v_max_f32_e32 v127, v127, v129
	ds_bpermute_b32 v129, v144, v127
	s_waitcnt lgkmcnt(0)
	v_max3_f32 v131, v128, v127, v129
	v_sub_f32_e32 v127, v128, v131
	v_exp_f32_e32 v128, v127
	s_nop 0
	v_pk_mul_f32 v[58:59], v[58:59], v[128:129] op_sel_hi:[1,0]
	v_pk_mul_f32 v[56:57], v[56:57], v[128:129] op_sel_hi:[1,0]
	v_pk_mul_f32 v[50:51], v[50:51], v[128:129] op_sel_hi:[1,0]
	v_pk_mul_f32 v[48:49], v[48:49], v[128:129] op_sel_hi:[1,0]
	v_pk_mul_f32 v[42:43], v[42:43], v[128:129] op_sel_hi:[1,0]
	v_pk_mul_f32 v[40:41], v[40:41], v[128:129] op_sel_hi:[1,0]
	v_pk_mul_f32 v[34:35], v[34:35], v[128:129] op_sel_hi:[1,0]
	v_pk_mul_f32 v[32:33], v[32:33], v[128:129] op_sel_hi:[1,0]
	v_pk_mul_f32 v[26:27], v[26:27], v[128:129] op_sel_hi:[1,0]
	v_pk_mul_f32 v[24:25], v[24:25], v[128:129] op_sel_hi:[1,0]
	v_mov_b32_e32 v128, v131
	v_xor_b32_e32 v152, 0x80000000, v131
	v_xor_b32_e32 v153, 0x80000000, v131
	v_xor_b32_e32 v154, 0x80000000, v131
	v_xor_b32_e32 v155, 0x80000000, v131
	v_pk_add_f32 v[92:93], v[92:93], v[130:131] op_sel_hi:[1,0] neg_lo:[0,1] neg_hi:[0,1]
	v_pk_add_f32 v[94:95], v[94:95], v[130:131] op_sel_hi:[1,0] neg_lo:[0,1] neg_hi:[0,1]
	v_pk_add_f32 v[96:97], v[96:97], v[130:131] op_sel_hi:[1,0] neg_lo:[0,1] neg_hi:[0,1]
	v_pk_add_f32 v[98:99], v[98:99], v[130:131] op_sel_hi:[1,0] neg_lo:[0,1] neg_hi:[0,1]
	v_pk_add_f32 v[100:101], v[100:101], v[130:131] op_sel_hi:[1,0] neg_lo:[0,1] neg_hi:[0,1]
	v_pk_add_f32 v[102:103], v[102:103], v[130:131] op_sel_hi:[1,0] neg_lo:[0,1] neg_hi:[0,1]
	v_pk_add_f32 v[104:105], v[104:105], v[130:131] op_sel_hi:[1,0] neg_lo:[0,1] neg_hi:[0,1]
	v_pk_add_f32 v[106:107], v[106:107], v[130:131] op_sel_hi:[1,0] neg_lo:[0,1] neg_hi:[0,1]
	v_pk_add_f32 v[76:77], v[76:77], v[128:129] op_sel_hi:[1,0] neg_lo:[0,1] neg_hi:[0,1]
	v_pk_add_f32 v[78:79], v[78:79], v[128:129] op_sel_hi:[1,0] neg_lo:[0,1] neg_hi:[0,1]
	v_pk_add_f32 v[80:81], v[80:81], v[128:129] op_sel_hi:[1,0] neg_lo:[0,1] neg_hi:[0,1]
	v_pk_add_f32 v[82:83], v[82:83], v[128:129] op_sel_hi:[1,0] neg_lo:[0,1] neg_hi:[0,1]
	v_pk_add_f32 v[84:85], v[84:85], v[128:129] op_sel_hi:[1,0] neg_lo:[0,1] neg_hi:[0,1]
	v_pk_add_f32 v[86:87], v[86:87], v[128:129] op_sel_hi:[1,0] neg_lo:[0,1] neg_hi:[0,1]
	v_pk_add_f32 v[88:89], v[88:89], v[128:129] op_sel_hi:[1,0] neg_lo:[0,1] neg_hi:[0,1]
	v_pk_add_f32 v[90:91], v[90:91], v[128:129] op_sel_hi:[1,0] neg_lo:[0,1] neg_hi:[0,1]
	s_branch .Lattn_sm
